# v14: grid barrier - L1/L2 invalidate issued at arrival (overlapped with the wait / the L2 writeback) instead of after the release, removing ~1.3us from every barrier's critical path
# speedup vs baseline: 1.0208x; 1.0170x over previous
.LBB0_320:
	v_readlane_b32 s4, v255, 6
	s_lshl_b32 s4, s4, 8
	v_readlane_b32 s6, v255, 9
	v_readlane_b32 s7, v255, 10
	s_add_u32 s4, s6, s4
	s_addc_u32 s5, s7, 0
	v_mov_b32_e32 v3, 0x1000
	v_mov_b32_e32 v5, 1
	global_atomic_add v5, v3, v5, s[4:5] offset:1024 sc0
	v_cvt_f32_u32_e32 v3, v4
	v_sub_u32_e32 v6, 0, v4
	v_rcp_iflag_f32_e32 v3, v3
	s_nop 0
	v_mul_f32_e32 v3, 0x4f7ffffe, v3
	v_cvt_u32_f32_e32 v3, v3
	v_mul_lo_u32 v6, v6, v3
	v_mul_hi_u32 v6, v3, v6
	v_add_u32_e32 v3, v3, v6
	s_waitcnt vmcnt(0)
	v_mul_hi_u32 v3, v5, v3
	v_mul_lo_u32 v6, v3, v4
	v_sub_u32_e32 v6, v5, v6
	v_add_u32_e32 v7, 1, v3
	v_cmp_ge_u32_e32 vcc, v6, v4
	v_add_u32_e32 v5, 1, v5
	s_nop 0
	v_cndmask_b32_e32 v3, v3, v7, vcc
	v_sub_u32_e32 v7, v6, v4
	v_cndmask_b32_e32 v6, v6, v7, vcc
	v_add_u32_e32 v7, 1, v3
	v_cmp_ge_u32_e32 vcc, v6, v4
	s_nop 1
	v_cndmask_b32_e32 v3, v3, v7, vcc
	v_mul_lo_u32 v6, v4, v3
	v_add_u32_e32 v4, v6, v4
	v_cmp_ne_u32_e32 vcc, v5, v4
	s_and_saveexec_b64 s[6:7], vcc
	s_xor_b64 s[6:7], exec, s[6:7]
	s_cbranch_execz .LBB0_334
	s_waitcnt lgkmcnt(0)
	v_mov_b32_e32 v2, 0x2000
	buffer_inv sc1
	global_load_dword v2, v2, s[4:5] offset:1024 sc1
	s_add_u32 s12, s4, 0x2400
	s_addc_u32 s13, s5, 0
	s_waitcnt vmcnt(0)
	v_cmp_eq_u32_e32 vcc, v2, v3
	s_and_saveexec_b64 s[8:9], vcc
	s_cbranch_execz .LBB0_333
	s_add_u32 s10, s46, 0x1ac0200
	s_addc_u32 s11, s47, 0
	s_mov_b32 s24, 1
	s_mov_b64 s[14:15], 0
	v_mov_b32_e32 v2, 0
	s_branch .LBB0_324

.LBB0_334:
	s_andn2_saveexec_b64 s[6:7], s[6:7]
	s_cbranch_execz .LBB0_352
	s_mov_b64 s[6:7], exec
	buffer_inv sc1
	buffer_wbl2 sc1
	s_waitcnt lgkmcnt(0)
	s_waitcnt vmcnt(0)
	v_mbcnt_lo_u32_b32 v3, s6, 0
	v_mbcnt_hi_u32_b32 v3, s7, v3
	v_cmp_eq_u32_e32 vcc, 0, v3
	s_and_saveexec_b64 s[8:9], vcc
	s_cbranch_execz .LBB0_337
	s_bcnt1_i32_b64 s6, s[6:7]
	v_mov_b32_e32 v4, 0x1ac3000
	v_mov_b32_e32 v5, s6
	global_atomic_add v4, v4, v5, s[46:47] offset:1024 sc0

.LBB0_351:
	s_or_b64 exec, exec, s[6:7]
	v_mov_b32_e32 v2, 0x2000
	v_mov_b32_e32 v3, 1
	global_atomic_add v2, v3, s[4:5] offset:1024

.LBB0_1439:
	v_readlane_b32 s4, v255, 6
	s_lshl_b32 s4, s4, 8
	v_readlane_b32 s10, v255, 9
	v_readlane_b32 s11, v255, 10
	s_add_u32 s4, s10, s4
	s_addc_u32 s5, s11, 0
	v_mov_b32_e32 v3, 0x1000
	v_mov_b32_e32 v5, 1
	global_atomic_add v5, v3, v5, s[4:5] offset:1024 sc0
	v_cvt_f32_u32_e32 v3, v4
	v_sub_u32_e32 v6, 0, v4
	v_rcp_iflag_f32_e32 v3, v3
	s_nop 0
	v_mul_f32_e32 v3, 0x4f7ffffe, v3
	v_cvt_u32_f32_e32 v3, v3
	v_mul_lo_u32 v6, v6, v3
	v_mul_hi_u32 v6, v3, v6
	v_add_u32_e32 v3, v3, v6
	s_waitcnt vmcnt(0)
	v_mul_hi_u32 v3, v5, v3
	v_mul_lo_u32 v6, v3, v4
	v_sub_u32_e32 v6, v5, v6
	v_add_u32_e32 v7, 1, v3
	v_cmp_ge_u32_e32 vcc, v6, v4
	v_add_u32_e32 v5, 1, v5
	s_nop 0
	v_cndmask_b32_e32 v3, v3, v7, vcc
	v_sub_u32_e32 v7, v6, v4
	v_cndmask_b32_e32 v6, v6, v7, vcc
	v_add_u32_e32 v7, 1, v3
	v_cmp_ge_u32_e32 vcc, v6, v4
	s_nop 1
	v_cndmask_b32_e32 v3, v3, v7, vcc
	v_mul_lo_u32 v6, v4, v3
	v_add_u32_e32 v4, v6, v4
	v_cmp_ne_u32_e32 vcc, v5, v4
	s_and_saveexec_b64 s[10:11], vcc
	s_xor_b64 s[10:11], exec, s[10:11]
	s_cbranch_execz .LBB0_1453
	s_waitcnt lgkmcnt(0)
	v_mov_b32_e32 v2, 0x2000
	buffer_inv sc1
	global_load_dword v2, v2, s[4:5] offset:1024 sc1
	s_add_u32 s16, s4, 0x2400
	s_addc_u32 s17, s5, 0
	s_waitcnt vmcnt(0)
	v_cmp_eq_u32_e32 vcc, v2, v3
	s_and_saveexec_b64 s[12:13], vcc
	s_cbranch_execz .LBB0_1452
	s_add_u32 s14, s46, 0x1ac0200
	s_addc_u32 s15, s47, 0
	s_mov_b32 s28, 1
	s_mov_b64 s[18:19], 0
	v_mov_b32_e32 v2, 0
	s_branch .LBB0_1443

.LBB0_1453:
	s_andn2_saveexec_b64 s[10:11], s[10:11]
	s_cbranch_execz .LBB0_1471
	s_mov_b64 s[10:11], exec
	buffer_inv sc1
	buffer_wbl2 sc1
	s_waitcnt lgkmcnt(0)
	s_waitcnt vmcnt(0)
	v_mbcnt_lo_u32_b32 v3, s10, 0
	v_mbcnt_hi_u32_b32 v3, s11, v3
	v_cmp_eq_u32_e32 vcc, 0, v3
	s_and_saveexec_b64 s[12:13], vcc
	s_cbranch_execz .LBB0_1456
	s_bcnt1_i32_b64 s10, s[10:11]
	v_mov_b32_e32 v4, 0x1ac3000
	v_mov_b32_e32 v5, s10
	global_atomic_add v4, v4, v5, s[46:47] offset:1024 sc0

.LBB0_1470:
	s_or_b64 exec, exec, s[10:11]
	v_mov_b32_e32 v2, 0x2000
	v_mov_b32_e32 v3, 1
	global_atomic_add v2, v3, s[4:5] offset:1024

.LBB0_1723:
	v_readlane_b32 s6, v255, 6
	s_lshl_b32 s6, s6, 8
	v_readlane_b32 s8, v255, 9
	v_readlane_b32 s9, v255, 10
	s_add_u32 s6, s8, s6
	s_addc_u32 s7, s9, 0
	v_mov_b32_e32 v19, 0x1000
	v_mov_b32_e32 v21, 1
	global_atomic_add v21, v19, v21, s[6:7] offset:1024 sc0
	v_cvt_f32_u32_e32 v19, v20
	v_sub_u32_e32 v22, 0, v20
	v_rcp_iflag_f32_e32 v19, v19
	s_nop 0
	v_mul_f32_e32 v19, 0x4f7ffffe, v19
	v_cvt_u32_f32_e32 v19, v19
	v_mul_lo_u32 v22, v22, v19
	v_mul_hi_u32 v22, v19, v22
	v_add_u32_e32 v19, v19, v22
	s_waitcnt vmcnt(0)
	v_mul_hi_u32 v19, v21, v19
	v_mul_lo_u32 v22, v19, v20
	v_sub_u32_e32 v22, v21, v22
	v_add_u32_e32 v23, 1, v19
	v_cmp_ge_u32_e32 vcc, v22, v20
	v_add_u32_e32 v21, 1, v21
	s_nop 0
	v_cndmask_b32_e32 v19, v19, v23, vcc
	v_sub_u32_e32 v23, v22, v20
	v_cndmask_b32_e32 v22, v22, v23, vcc
	v_add_u32_e32 v23, 1, v19
	v_cmp_ge_u32_e32 vcc, v22, v20
	s_nop 1
	v_cndmask_b32_e32 v19, v19, v23, vcc
	v_mul_lo_u32 v22, v20, v19
	v_add_u32_e32 v20, v22, v20
	v_cmp_ne_u32_e32 vcc, v21, v20
	s_and_saveexec_b64 s[8:9], vcc
	s_xor_b64 s[8:9], exec, s[8:9]
	s_cbranch_execz .LBB0_1737
	s_waitcnt lgkmcnt(0)
	v_mov_b32_e32 v18, 0x2000
	buffer_inv sc1
	global_load_dword v18, v18, s[6:7] offset:1024 sc1
	s_add_u32 s14, s6, 0x2400
	s_addc_u32 s15, s7, 0
	s_waitcnt vmcnt(0)
	v_cmp_eq_u32_e32 vcc, v18, v19
	s_and_saveexec_b64 s[10:11], vcc
	s_cbranch_execz .LBB0_1736
	s_add_u32 s12, s46, 0x1ac0200
	s_addc_u32 s13, s47, 0
	s_mov_b32 s26, 1
	s_mov_b64 s[16:17], 0
	v_mov_b32_e32 v18, 0
	s_branch .LBB0_1727

.LBB0_1737:
	s_andn2_saveexec_b64 s[8:9], s[8:9]
	s_cbranch_execz .LBB0_1755
	s_mov_b64 s[8:9], exec
	buffer_inv sc1
	buffer_wbl2 sc1
	s_waitcnt lgkmcnt(0)
	s_waitcnt vmcnt(0)
	v_mbcnt_lo_u32_b32 v19, s8, 0
	v_mbcnt_hi_u32_b32 v19, s9, v19
	v_cmp_eq_u32_e32 vcc, 0, v19
	s_and_saveexec_b64 s[10:11], vcc
	s_cbranch_execz .LBB0_1740
	s_bcnt1_i32_b64 s8, s[8:9]
	v_mov_b32_e32 v20, 0x1ac3000
	v_mov_b32_e32 v21, s8
	global_atomic_add v20, v20, v21, s[46:47] offset:1024 sc0

.LBB0_1754:
	s_or_b64 exec, exec, s[8:9]
	v_mov_b32_e32 v18, 0x2000
	v_mov_b32_e32 v19, 1
	global_atomic_add v18, v19, s[6:7] offset:1024

.LBB0_1807:
	v_readlane_b32 s4, v255, 6
	s_lshl_b32 s4, s4, 8
	v_readlane_b32 s6, v255, 9
	v_readlane_b32 s7, v255, 10
	s_add_u32 s4, s6, s4
	s_addc_u32 s5, s7, 0
	v_mov_b32_e32 v1, 0x1000
	v_mov_b32_e32 v3, 1
	global_atomic_add v3, v1, v3, s[4:5] offset:1024 sc0
	v_cvt_f32_u32_e32 v1, v2
	v_sub_u32_e32 v4, 0, v2
	v_rcp_iflag_f32_e32 v1, v1
	s_nop 0
	v_mul_f32_e32 v1, 0x4f7ffffe, v1
	v_cvt_u32_f32_e32 v1, v1
	v_mul_lo_u32 v4, v4, v1
	v_mul_hi_u32 v4, v1, v4
	v_add_u32_e32 v1, v1, v4
	s_waitcnt vmcnt(0)
	v_mul_hi_u32 v1, v3, v1
	v_mul_lo_u32 v4, v1, v2
	v_sub_u32_e32 v4, v3, v4
	v_add_u32_e32 v5, 1, v1
	v_cmp_ge_u32_e32 vcc, v4, v2
	v_add_u32_e32 v3, 1, v3
	s_nop 0
	v_cndmask_b32_e32 v1, v1, v5, vcc
	v_sub_u32_e32 v5, v4, v2
	v_cndmask_b32_e32 v4, v4, v5, vcc
	v_add_u32_e32 v5, 1, v1
	v_cmp_ge_u32_e32 vcc, v4, v2
	s_nop 1
	v_cndmask_b32_e32 v1, v1, v5, vcc
	v_mul_lo_u32 v4, v2, v1
	v_add_u32_e32 v2, v4, v2
	v_cmp_ne_u32_e32 vcc, v3, v2
	s_and_saveexec_b64 s[6:7], vcc
	s_xor_b64 s[6:7], exec, s[6:7]
	s_cbranch_execz .LBB0_1821
	s_waitcnt lgkmcnt(0)
	v_mov_b32_e32 v0, 0x2000
	buffer_inv sc1
	global_load_dword v0, v0, s[4:5] offset:1024 sc1
	s_add_u32 s12, s4, 0x2400
	s_addc_u32 s13, s5, 0
	s_waitcnt vmcnt(0)
	v_cmp_eq_u32_e32 vcc, v0, v1
	s_and_saveexec_b64 s[8:9], vcc
	s_cbranch_execz .LBB0_1820
	s_add_u32 s10, s46, 0x1ac0200
	s_addc_u32 s11, s47, 0
	s_mov_b32 s24, 1
	s_mov_b64 s[14:15], 0
	v_mov_b32_e32 v0, 0
	s_branch .LBB0_1811

.LBB0_1821:
	s_andn2_saveexec_b64 s[6:7], s[6:7]
	s_cbranch_execz .LBB0_1839
	s_mov_b64 s[6:7], exec
	buffer_inv sc1
	buffer_wbl2 sc1
	s_waitcnt lgkmcnt(0)
	s_waitcnt vmcnt(0)
	v_mbcnt_lo_u32_b32 v1, s6, 0
	v_mbcnt_hi_u32_b32 v1, s7, v1
	v_cmp_eq_u32_e32 vcc, 0, v1
	s_and_saveexec_b64 s[8:9], vcc
	s_cbranch_execz .LBB0_1824
	s_bcnt1_i32_b64 s6, s[6:7]
	v_mov_b32_e32 v2, 0x1ac3000
	v_mov_b32_e32 v3, s6
	global_atomic_add v2, v2, v3, s[46:47] offset:1024 sc0

.LBB0_1838:
	s_or_b64 exec, exec, s[6:7]
	v_mov_b32_e32 v0, 0x2000
	v_mov_b32_e32 v1, 1
	global_atomic_add v0, v1, s[4:5] offset:1024
